# attention: next-tile K/V LDS staging writes issued inside the compute block (overlap with softmax VALU) instead of after it
# baseline (speedup 1.0000x reference)
.LBB0_2407:
	s_or_b64 exec, exec, s[26:27]
	s_mov_b32 s101, 0
	global_load_dwordx4 v[96:99], v[106:107], off
	s_add_i32 s26, s13, -1
	s_and_b32 s28, s13, 1
	v_cmp_le_i32_e32 vcc, s26, v114
	s_and_saveexec_b64 s[26:27], vcc
	s_cbranch_execz .LBB0_2409
	s_mul_i32 s29, s28, 0x5800
	s_add_i32 s29, s29, 0
	v_add3_u32 v119, s29, v116, v192
	ds_read_b128 v[32:35], v119 offset:6656
	ds_read_b128 v[36:39], v119
	ds_read_b128 v[120:123], v119 offset:32
	ds_read_b128 v[124:127], v119 offset:6688
	s_waitcnt lgkmcnt(2)
	v_mfma_f32_32x32x16_bf16 v[48:63], v[36:39], v[88:91], v[136:151]
	v_mfma_f32_32x32x16_bf16 v[32:47], v[32:35], v[88:91], v[136:151]
	s_waitcnt lgkmcnt(1)
	v_mfma_f32_32x32x16_bf16 v[48:63], v[120:123], v[84:87], v[48:63]
	s_waitcnt lgkmcnt(0)
	v_mfma_f32_32x32x16_bf16 v[32:47], v[124:127], v[84:87], v[32:47]
	ds_read_b128 v[120:123], v119 offset:64
	ds_read_b128 v[124:127], v119 offset:6720
	s_waitcnt lgkmcnt(1)
	v_mfma_f32_32x32x16_bf16 v[48:63], v[120:123], v[80:83], v[48:63]
	s_waitcnt lgkmcnt(0)
	v_mfma_f32_32x32x16_bf16 v[32:47], v[124:127], v[80:83], v[32:47]
	ds_read_b128 v[120:123], v119 offset:96
	ds_read_b128 v[124:127], v119 offset:6752
	s_waitcnt lgkmcnt(1)
	v_mfma_f32_32x32x16_bf16 v[48:63], v[120:123], v[76:79], v[48:63]
	s_waitcnt lgkmcnt(0)
	v_mfma_f32_32x32x16_bf16 v[32:47], v[124:127], v[76:79], v[32:47]
	ds_read_b128 v[120:123], v119 offset:128
	ds_read_b128 v[124:127], v119 offset:6784
	s_waitcnt lgkmcnt(1)
	v_mfma_f32_32x32x16_bf16 v[48:63], v[120:123], v[72:75], v[48:63]
	s_waitcnt lgkmcnt(0)
	v_mfma_f32_32x32x16_bf16 v[32:47], v[124:127], v[72:75], v[32:47]
	ds_read_b128 v[120:123], v119 offset:160
	ds_read_b128 v[124:127], v119 offset:6816
	s_waitcnt lgkmcnt(1)
	v_mfma_f32_32x32x16_bf16 v[48:63], v[120:123], v[68:71], v[48:63]
	s_waitcnt lgkmcnt(0)
	v_mfma_f32_32x32x16_bf16 v[32:47], v[124:127], v[68:71], v[32:47]
	v_add3_u32 v168, s29, v117, v192
	ds_read_b128 v[152:155], v168 offset:13312
	ds_read_b128 v[156:159], v168 offset:17920
	ds_read_b128 v[160:163], v168 offset:13344
	ds_read_b128 v[164:167], v168 offset:17952
	ds_read_b128 v[128:131], v168 offset:13376
	ds_read_b128 v[132:135], v168 offset:17984
	ds_read_b128 v[172:175], v168 offset:13408
	ds_read_b128 v[176:179], v168 offset:18016
	s_nop 1
	v_max_f32_e32 v119, v48, v49
	v_max3_f32 v119, v119, v50, v51
	v_max3_f32 v119, v119, v52, v53
	v_max3_f32 v119, v119, v54, v55
	v_max3_f32 v119, v119, v56, v57
	v_max3_f32 v119, v119, v58, v59
	v_max3_f32 v119, v119, v60, v61
	v_max3_f32 v119, v119, v62, v63
	v_max3_f32 v119, v119, v32, v33
	v_max3_f32 v119, v119, v34, v35
	v_max3_f32 v119, v119, v36, v37
	v_max3_f32 v119, v119, v38, v39
	v_max3_f32 v119, v119, v40, v41
	v_max3_f32 v119, v119, v42, v43
	v_max3_f32 v119, v119, v44, v45
	v_max3_f32 v119, v119, v46, v47
	v_cmp_lt_f32_e32 vcc, 0x41000000, v119
	s_cbranch_vccnz .Lattn_rare
.Lattn_common:
	v_exp_f32_e32 v48, v48
	v_exp_f32_e32 v49, v49
	v_exp_f32_e32 v50, v50
	v_exp_f32_e32 v51, v51
	v_add_f32_e32 v169, v48, v49
	v_exp_f32_e32 v52, v52
	v_add_f32_e32 v169, v50, v169
	v_exp_f32_e32 v53, v53
	v_add_f32_e32 v169, v51, v169
	v_exp_f32_e32 v54, v54
	v_add_f32_e32 v169, v52, v169
	v_exp_f32_e32 v55, v55
	v_add_f32_e32 v169, v53, v169
	v_add_f32_e32 v169, v54, v169
	v_cvt_pk_bf16_f32 v180, v48, v49
	v_add_f32_e32 v169, v55, v169
	v_cvt_pk_bf16_f32 v181, v50, v51
	v_cvt_pk_bf16_f32 v182, v52, v53
	v_cvt_pk_bf16_f32 v183, v54, v55
	v_exp_f32_e32 v56, v56
	v_exp_f32_e32 v57, v57
	s_waitcnt lgkmcnt(6)
	v_mfma_f32_32x32x16_bf16 v[16:31], v[152:155], v[180:183], v[16:31]
	v_mfma_f32_32x32x16_bf16 v[0:15], v[156:159], v[180:183], v[0:15]
	v_exp_f32_e32 v58, v58
	v_add_f32_e32 v169, v56, v169
	v_exp_f32_e32 v59, v59
	v_add_f32_e32 v169, v57, v169
	v_exp_f32_e32 v60, v60
	v_add_f32_e32 v169, v58, v169
	v_exp_f32_e32 v61, v61
	v_add_f32_e32 v169, v59, v169
	v_exp_f32_e32 v62, v62
	v_add_f32_e32 v169, v60, v169
	v_exp_f32_e32 v63, v63
	v_add_f32_e32 v169, v61, v169
	v_add_f32_e32 v169, v62, v169
	v_cvt_pk_bf16_f32 v184, v56, v57
	v_add_f32_e32 v169, v63, v169
	v_cvt_pk_bf16_f32 v185, v58, v59
	v_cvt_pk_bf16_f32 v186, v60, v61
	v_cvt_pk_bf16_f32 v187, v62, v63
	v_exp_f32_e32 v32, v32
	v_exp_f32_e32 v33, v33
	s_waitcnt lgkmcnt(4)
	v_mfma_f32_32x32x16_bf16 v[16:31], v[160:163], v[184:187], v[16:31]
	v_mfma_f32_32x32x16_bf16 v[0:15], v[164:167], v[184:187], v[0:15]
	v_exp_f32_e32 v34, v34
	v_add_f32_e32 v169, v32, v169
	v_exp_f32_e32 v35, v35
	v_add_f32_e32 v169, v33, v169
	v_exp_f32_e32 v36, v36
	v_add_f32_e32 v169, v34, v169
	v_exp_f32_e32 v37, v37
	v_add_f32_e32 v169, v35, v169
	v_exp_f32_e32 v38, v38
	v_add_f32_e32 v169, v36, v169
	v_exp_f32_e32 v39, v39
	v_add_f32_e32 v169, v37, v169
	v_add_f32_e32 v169, v38, v169
	v_cvt_pk_bf16_f32 v180, v32, v33
	v_add_f32_e32 v169, v39, v169
	v_cvt_pk_bf16_f32 v181, v34, v35
	v_cvt_pk_bf16_f32 v182, v36, v37
	v_cvt_pk_bf16_f32 v183, v38, v39
	v_exp_f32_e32 v40, v40
	v_exp_f32_e32 v41, v41
	s_waitcnt lgkmcnt(2)
	v_mfma_f32_32x32x16_bf16 v[16:31], v[128:131], v[180:183], v[16:31]
	v_mfma_f32_32x32x16_bf16 v[0:15], v[132:135], v[180:183], v[0:15]
	s_sub_i32 s100, 0x5800, s29
	v_add_u32_e32 v188, s100, v112
	v_add_u32_e32 v189, s100, v111
	v_add_u32_e32 v190, s100, v113
	s_waitcnt vmcnt(1)
	ds_write_b128 v188, v[92:95]
	s_mov_b64 vcc, exec
	s_and_b64 exec, exec, s[6:7]
	ds_write_b128 v189, v[64:67]
	s_mov_b64 exec, vcc
	s_waitcnt vmcnt(0)
	ds_write_b128 v190, v[96:99] offset:13312
	s_mov_b32 s101, 1
	v_exp_f32_e32 v42, v42
	v_add_f32_e32 v169, v40, v169
	v_exp_f32_e32 v43, v43
	v_add_f32_e32 v169, v41, v169
	v_exp_f32_e32 v44, v44
	v_add_f32_e32 v169, v42, v169
	v_exp_f32_e32 v45, v45
	v_add_f32_e32 v169, v43, v169
	v_exp_f32_e32 v46, v46
	v_add_f32_e32 v169, v44, v169
	v_exp_f32_e32 v47, v47
	v_add_f32_e32 v169, v45, v169
	v_add_f32_e32 v169, v46, v169
	v_cvt_pk_bf16_f32 v184, v40, v41
	v_add_f32_e32 v169, v47, v169
	v_cvt_pk_bf16_f32 v185, v42, v43
	v_cvt_pk_bf16_f32 v186, v44, v45
	v_cvt_pk_bf16_f32 v187, v46, v47
	v_add_f32_e32 v115, v115, v169
	s_nop 0
	s_waitcnt lgkmcnt(0)
	v_mfma_f32_32x32x16_bf16 v[16:31], v[172:175], v[184:187], v[16:31]
	v_mfma_f32_32x32x16_bf16 v[0:15], v[176:179], v[184:187], v[0:15]
	s_branch .Lattn_blk_end

.Lattn_blk_end:
.LBB0_2409:
	s_or_b64 exec, exec, s[26:27]
	s_cmp_lg_u32 s101, 0
	s_cbranch_scc1 .Lattn_skip_writes
	s_xor_b32 s26, s28, 1
	s_mulk_i32 s26, 0x5800
	s_add_i32 s28, s26, 0
	v_add_u32_e32 v32, s28, v112
	s_waitcnt vmcnt(1)
	ds_write_b128 v32, v[92:95]
	s_and_saveexec_b64 s[26:27], s[6:7]
	v_add_u32_e32 v32, s28, v111
	ds_write_b128 v32, v[64:67]
	s_or_b64 exec, exec, s[26:27]
	v_add_u32_e32 v32, s28, v113
	s_waitcnt vmcnt(0)
	ds_write_b128 v32, v[96:99] offset:13312
.Lattn_skip_writes:
	s_add_i32 s28, s13, 1
	s_add_i32 s26, s1, s28
	v_lshl_add_u64 v[106:107], v[106:107], 0, s[80:81]
	s_cmp_eq_u32 s26, 1
	v_lshl_add_u64 v[108:109], v[108:109], 0, s[70:71]
	s_waitcnt lgkmcnt(0)
	s_barrier
	s_cbranch_scc1 .LBB0_2413
	s_mov_b32 s13, s28
	global_load_dwordx4 v[92:95], v[108:109], off
	s_and_saveexec_b64 s[26:27], s[6:7]
	s_cbranch_execnz .LBB0_2406
	s_branch .LBB0_2407
